# retention wave roles remapped so every SIMD carries 5 key tiles per chunk (waves 4-7 take query slice 3 - (w&3))
# baseline (speedup 1.0000x reference)
;     DEVINL bf16_t* BVT() const { return (bf16_t*)(ws + OFF_BVT); }
;     DEVINL bf16_t* BKT() const { return (bf16_t*)(ws + OFF_BKT); }
;     DEVINL bf16_t* Y() const { return (bf16_t*)(ws + OFF_Y); }
; #define TID (opq_v((int)threadIdx.x))
; DEVINL bf16_t f2bf(float f) { return (bf16_t)(cvt_pk_bf16(f, 0.f) & 0xffffu); }
; DEVINL float fexp2(float x) { return __builtin_amdgcn_exp2f(x); }
; DEVINL float flog2(float x) { return __builtin_amdgcn_logf(x); }
; DEVINL void ret_block(const Ctx& c, int b, int hd, unsigned char* lds) {
;     ...
;     const int tid = TID, lane = tid & 63, w = tid >> 6, r = lane & 31, h = lane >> 5;
;     const int qs = w & 3, dh = w >> 2, dvt = w >> 1, dt = w & 1;
;     const float lg2 = flog2(1.f - fexp2(-5.f - (float)hd));
;     const float gam = fexp2(lg2), gam128 = fexp2(lg2 * 128.f);
;     f32x16 sacc;
; #pragma unroll
;     for (int i = 0; i < 16; ++i) sacc[i] = 0.f;
;     const bf16_t* vtb = c.BVT() + (size_t)(b * 512 + hd * 128) * L;
;     const bf16_t* ktb = c.BKT() + (size_t)(b * 256 + hd * 64) * L;
;     bf16_t* Y = c.Y() + (size_t)T * 512;
;     for (int ch = 0; ch < L / 128; ++ch) {
;         const int t0 = b * L + ch * 128, p0 = ch * 128;
;         __syncthreads();
; #pragma unroll
;         for (int i = 0; i < 16; ++i) {
;             const int dv = dvt * 32 + (i & 3) + 8 * (i >> 2) + 4 * h;
;             ST[dv * 72 + dt * 32 + r] = f2bf(sacc[i]);
;         }
;         __syncthreads();
;         const int ql = qs * 32 + r;
.LBB0_266:
	s_and_b64 vcc, exec, s[0:1]
	s_cbranch_vccz .LBB0_275
	s_and_b32 s12, s95, 3
	s_waitcnt vmcnt(0)
	v_cvt_f32_ubyte0_e32 v0, s12
	v_sub_f32_e32 v0, 0xc0a00000, v0
	v_exp_f32_e32 v0, v0
	v_mov_b32_e32 v2, v160
	s_sub_i32 s0, s95, 64
	v_sub_f32_e32 v0, 1.0, v0
	v_log_f32_e32 v93, v0
	v_ashrrev_i32_e32 v0, 6, v2
	v_and_b32_e32 v6, 1, v0
	v_lshlrev_b32_e32 v0, 5, v0
	v_and_b32_e32 v3, 31, v2
	v_and_b32_e32 v10, 0x60, v0
	v_bfe_u32 v231, v0, 7, 1
	v_mul_u32_u24_e32 v231, 0x60, v231
	v_xor_b32_e32 v10, v10, v231
	v_mul_f32_e32 v1, 0x43000000, v93
	v_or_b32_e32 v92, v10, v3
	v_exp_f32_e32 v88, v1
	v_lshlrev_b32_e32 v1, 6, v6
	v_lshlrev_b32_e32 v9, 1, v3
	v_cvt_f32_ubyte0_e32 v0, v92
	v_add3_u32 v9, 0, v1, v9
	v_mul_f32_e32 v0, v93, v0
	v_and_b32_e32 v1, 64, v162
	s_lshr_b32 s13, s0, 2
	v_ashrrev_i32_e32 v5, 8, v2
	s_lshl_b32 s14, s12, 7
	v_exp_f32_e32 v98, v0
	v_xor_b32_e32 v0, 32, v162
	v_add_u32_e32 v1, 64, v1
	s_lshl_b32 s4, s12, 8
	v_readlane_b32 s5, v247, 53
	v_bfe_u32 v4, v2, 5, 1
	v_ashrrev_i32_e32 v7, 2, v2
	v_lshlrev_b32_e32 v94, 6, v5
	v_cmp_lt_i32_e32 vcc, v0, v1
	s_add_u32 s4, s5, s4
	v_readlane_b32 s5, v247, 54
	v_and_b32_e32 v8, 0xffffffe0, v7
	v_lshlrev_b32_e32 v90, 2, v4
	v_cndmask_b32_e32 v0, v162, v0, vcc
	v_ashrrev_i32_e32 v95, 31, v94
	s_addc_u32 s5, s5, 0
	v_lshlrev_b32_e32 v64, 3, v4
	v_or_b32_e32 v11, v94, v3
	v_lshlrev_b32_e32 v96, 4, v4
	v_lshlrev_b32_e32 v122, 2, v0
	v_cmp_eq_u32_e64 s[0:1], 0, v4
	v_lshl_add_u64 v[0:1], v[94:95], 1, s[4:5]
	v_lshl_or_b32 v4, v6, 5, v3
	v_or_b32_e32 v6, v90, v8
	s_movk_i32 s4, 0x90
	v_mul_lo_u32 v6, v6, s4
	v_mul_lo_u32 v8, v11, s4
	s_add_u32 s4, s26, s14
	s_addc_u32 s5, s27, 0
	v_mov_b32_e32 v97, v65
	s_movk_i32 s15, 0x1100
	v_lshl_add_u64 v[104:105], s[4:5], 0, v[96:97]
	v_lshl_add_u64 v[106:107], v[0:1], 0, v[64:65]
	v_mad_i64_i32 v[0:1], s[4:5], v11, s15, 0
	s_mul_i32 s4, s13, 0x110000
	s_mul_i32 s5, s12, 0x44000
	s_add_i32 s66, s4, s5
	s_lshl_b64 s[4:5], s[66:67], 1
	v_readlane_b32 s8, v246, 26
	s_add_u32 s8, s8, s4
	v_readlane_b32 s9, v246, 29
	v_or_b32_e32 v0, v0, v64
	s_addc_u32 s9, s9, s5
	v_lshl_add_u64 v[108:109], s[8:9], 0, v[0:1]
	v_or_b32_e32 v0, 32, v11
	v_mad_i64_i32 v[0:1], s[10:11], v0, s15, 0
	v_or_b32_e32 v0, v0, v64
	v_lshl_add_u64 v[110:111], s[8:9], 0, v[0:1]
	s_movk_i32 s8, 0xffe0
	v_bfi_b32 v2, s8, v7, v2
	v_readlane_b32 s8, v246, 27
	v_readlane_b32 s9, v246, 28
	s_add_u32 s4, s8, s4
	s_addc_u32 s5, s9, s5
	v_mov_b64_e32 v[0:1], s[4:5]
	v_mad_i64_i32 v[112:113], s[4:5], v2, s15, v[0:1]
	s_mul_i32 s4, s13, 0x88000
	s_mul_i32 s12, s12, 0x22000
	v_exp_f32_e32 v86, v93
	s_add_i32 s66, s4, s12
	s_lshl_b64 s[4:5], s[66:67], 1
	v_mul_u32_u24_e32 v4, 0x880, v4
	s_add_u32 s4, s8, s4
	s_mul_i32 s6, s13, 0x880
	v_add_u32_e32 v12, 0, v96
	v_lshl_add_u32 v123, v92, 2, 0
	v_lshlrev_b32_e32 v5, 9, v5
	v_sub_u32_e32 v126, 0, v64
	v_lshlrev_b32_e32 v64, 1, v4
	s_addc_u32 s5, s9, s5
	v_mov_b32_e32 v0, 0
	s_mov_b32 s7, 0
	v_mov_b32_e32 v99, v98
	v_mov_b32_e32 v100, v86
	v_mov_b32_e32 v101, v86
	v_mov_b32_e32 v91, v92
	v_mov_b32_e32 v102, v88
	v_mov_b32_e32 v103, v88
	v_add_u32_e32 v124, 32, v10
	v_or_b32_e32 v125, s6, v3
	v_lshl_add_u64 v[114:115], s[4:5], 0, v[64:65]
	v_add_u32_e32 v127, v9, v6
	v_add_u32_e32 v128, v12, v8
	v_add_u32_e32 v129, v123, v5
	s_lshl_b32 s66, s14, 1
	v_mov_b32_e32 v1, v0
	v_mov_b32_e32 v2, v0
	v_mov_b32_e32 v3, v0
	v_mov_b32_e32 v4, v0
	v_mov_b32_e32 v5, v0
	v_mov_b32_e32 v6, v0
	v_mov_b32_e32 v7, v0
	v_mov_b32_e32 v8, v0
	v_mov_b32_e32 v9, v0
	v_mov_b32_e32 v10, v0
	v_mov_b32_e32 v11, v0
	v_mov_b32_e32 v12, v0
	v_mov_b32_e32 v13, v0
	v_mov_b32_e32 v14, v0
	v_mov_b32_e32 v15, v0
	v_lshlrev_b32_e32 v206, 1, v94
	v_add_u32_e32 v206, s14, v206
	v_lshlrev_b32_e32 v207, 1, v90
	v_sub_u32_e32 v206, v206, v207
	v_add_u32_e32 v206, 0x400, v206
	v_mov_b32_e32 v207, 0
